# layer-end barrier skips the L2 write-back for layers 0..2; weight-converter workgroups write back the L2 themselves before the up->down barrier
# baseline (speedup 1.0000x reference)
.LBB0_847:
	s_waitcnt vmcnt(0)
	v_readlane_b32 s0, v255, 6
	v_readlane_b32 s1, v255, 7
	s_and_b64 vcc, exec, s[0:1]
	s_barrier
	s_cbranch_vccnz .LBB0_901
	v_mbcnt_lo_u32_b32 v0, -1, 0
	v_mbcnt_hi_u32_b32 v0, -1, v0
	s_nop 0
	v_cmp_eq_u32_e32 vcc, 0, v0
	s_and_saveexec_b64 s[4:5], vcc
	s_cbranch_execz .LBB0_900
	s_cmp_eq_u32 s33, 0x100
	s_cbranch_scc0 .Llb_skip_b5
	v_readlane_b32 s0, v253, 35
	v_readlane_b32 s1, v253, 36
	s_and_b32 s6, s2, 7
	s_lshl_b32 s6, s6, 8
	s_nop 3
	s_add_u32 s0, s0, s6
	s_addc_u32 s1, s1, 0
	s_add_u32 s0, s0, 0xf3700
	s_addc_u32 s1, s1, 0
	s_cmp_lt_u32 s2, 0x80
	s_cbranch_scc1 .Lb5_noconvwb
	buffer_wbl2 sc1
	s_waitcnt vmcnt(0)
.Lb5_noconvwb:
	v_mov_b32_e32 v0, 0x2010c
	ds_read_b32 v1, v0
	v_mov_b32_e32 v2, 1
	global_atomic_add v177, v2, s[0:1]
	s_waitcnt lgkmcnt(0)
	v_add_u32_e32 v1, 1, v1
	ds_write_b32 v0, v1
	v_lshlrev_b32_e32 v1, 5, v1
	s_mov_b32 s12, 0

.LBB0_987:
	s_mov_b64 s[0:1], exec
	s_cmp_eq_u32 s33, 0x100
	s_cbranch_scc0 .Lb6_wb
	v_readlane_b32 s6, v255, 5
	s_nop 3
	s_cmp_eq_u32 s6, 3
	s_cbranch_scc0 .Lb6_nowb
.Lb6_wb:
	buffer_wbl2 sc1
.Lb6_nowb:
	s_waitcnt lgkmcnt(0)
	s_waitcnt vmcnt(0)
	v_mbcnt_lo_u32_b32 v1, s0, 0
	v_mbcnt_hi_u32_b32 v1, s1, v1
	v_cmp_eq_u32_e32 vcc, 0, v1
	s_and_saveexec_b64 s[6:7], vcc
	s_cbranch_execz .LBB0_989
	s_bcnt1_i32_b64 s0, s[0:1]
	v_mov_b32_e32 v2, s0
	v_readlane_b32 s0, v253, 15
	v_readlane_b32 s1, v253, 16
	s_nop 4
	global_atomic_add v2, v177, v2, s[0:1] sc0
.LBB0_989:
	s_or_b64 exec, exec, s[6:7]
	s_waitcnt vmcnt(0)
	v_readfirstlane_b32 s0, v2
	v_cvt_f32_u32_e32 v2, v0
	v_sub_u32_e32 v3, 0, v0
	v_add_u32_e32 v1, s0, v1
	v_readlane_b32 s0, v253, 17
	v_rcp_iflag_f32_e32 v2, v2
	v_readlane_b32 s1, v253, 18
	s_mov_b64 s[28:29], -1
	v_mul_f32_e32 v2, 0x4f7ffffe, v2
	v_cvt_u32_f32_e32 v2, v2
	v_mul_lo_u32 v3, v3, v2
	v_mul_hi_u32 v3, v2, v3
	v_add_u32_e32 v2, v2, v3
	v_mul_hi_u32 v2, v1, v2
	v_mul_lo_u32 v3, v2, v0
	v_sub_u32_e32 v3, v1, v3
	v_cmp_ge_u32_e32 vcc, v3, v0
	v_add_u32_e32 v4, 1, v2
	v_add_u32_e32 v1, 1, v1
	v_cndmask_b32_e32 v2, v2, v4, vcc
	v_sub_u32_e32 v4, v3, v0
	v_cndmask_b32_e32 v3, v3, v4, vcc
	v_cmp_ge_u32_e32 vcc, v3, v0
	v_add_u32_e32 v3, 1, v2
	s_nop 0
	v_cndmask_b32_e32 v2, v2, v3, vcc
	v_mul_lo_u32 v3, v0, v2
	v_add_u32_e32 v0, v3, v0
	v_cmp_ne_u32_e32 vcc, v1, v0
	v_mov_b64_e32 v[0:1], s[0:1]
	s_and_saveexec_b64 s[0:1], vcc
	s_cbranch_execz .LBB0_1001
	v_readlane_b32 s6, v253, 17
	v_readlane_b32 s7, v253, 18
	s_nop 4
	global_load_dword v0, v177, s[6:7] sc1
	s_mov_b64 s[6:7], 0
	s_waitcnt vmcnt(0)
	v_cmp_eq_u32_e32 vcc, v0, v2
	s_and_saveexec_b64 s[28:29], vcc
	s_cbranch_execz .LBB0_1000
	s_mov_b32 s12, 1
	s_mov_b64 s[30:31], 0
	s_branch .LBB0_993
